# late ticket prefetch with counted waits: the dequeue waits only for the prefetched atomic (vmcnt 4/8), not for the item's output store acks
# speedup vs baseline: 1.0099x; 1.0099x over previous
; #define PH_BEGIN const int tid = otid(); const int G = gridDim.x; const int bid = osi((int)blockIdx.x); unsigned char* ws = osp(P.ws); float* out = osp(P.out); unsigned char* U = ws + WS_U; (void)tid; (void)G; (void)bid; (void)out; (void)U;
; __global__ void __launch_bounds__(512, 2) mega(Params P) {
;     ...
;                 PH_BEGIN
;                 __syncthreads();
;                 if (tid == 0) *sitem = (int)atomicAdd(WSP(unsigned, WS_CTL) + 3600 + l + 2 * rep, 1u);
;                 __syncthreads();
;                 const int it = *sitem;
;                 if (it >= 1280) break;
.Ldq_dyn:
	s_cmp_eq_u32 s99, 0
	s_cbranch_scc1 .Ldq_atomic
	s_cmp_eq_u32 s99, 2
	s_mov_b32 s99, 0
	s_cbranch_scc1 .Ldq_w8
	s_waitcnt vmcnt(4)
	s_branch .Ldq_got
.Ldq_w8:
	s_waitcnt vmcnt(8)
.Ldq_got:
	v_readfirstlane_b32 s2, v250
	s_addk_i32 s2, 0x1e0
	s_branch .Ldq_pub

; DI u32x2 pack4(const float* v) { u32x2 w; w.x = pk2(v[0], v[1]); w.y = pk2(v[2], v[3]); return w; }
; DI void sb_item(int g_wave, LAS unsigned char* lds, const bf16_t* SQ, const float* kf, const float* vf, bf16_t* MIX, int kvbase, int qrow0, int qpos0, int nq, int head,
;                 const float* ck, const float* cvp) {
;     ...
;     if (active) {
;         bf16_t* orow_ = MIX + (size_t)(qrow0 + 32 * w + r) * 1024 + 768 + head * 64;
; #pragma unroll
;         for (int g = 0; g < 4; ++g) {
;             float a[4], b[4];
; #pragma unroll
;             for (int j = 0; j < 4; ++j) { a[j] = o0[4 * g + j]; b[j] = o1[4 * g + j]; }
;             *(u32x2*)(orow_ + 8 * g + 4 * h) = pack4(a);
;             *(u32x2*)(orow_ + 32 + 8 * g + 4 * h) = pack4(b);
;         }
; __global__ void __launch_bounds__(512, 2) mega(Params P) {
;     ...
;                 if (tid == 0) *sitem = (int)atomicAdd(WSP(unsigned, WS_CTL) + 3600 + l + 2 * rep, 1u);
.LBB0_944:
	s_andn2_b64 vcc, exec, s[30:31]
	s_cbranch_vccnz .LBB0_946
	s_cmp_lg_u32 s21, 0
	s_cbranch_scc1 .Lpf_skip_sb
	v_readlane_b32 s100, v254, 25
	v_readlane_b32 s101, v254, 26
	s_add_u32 s100, s100, s34
	s_addc_u32 s101, s101, s35
	s_mov_b64 exec, 1
	v_mov_b32_e32 v251, 1
	v_mov_b32_e32 v249, 0x3000
	global_atomic_add v250, v249, v251, s[100:101] offset:2112 sc0
	s_mov_b64 exec, -1
	s_mov_b32 s99, 2
